# norm rows loop: non-temporal hint also on the bf16 output row stores
# baseline (speedup 1.0000x reference)
.LBB0_180:
	v_readlane_b32 s0, v253, 39
	s_movk_i32 s3, 0x4000
	v_add_u32_e32 v0, 0xffffc000, v50
	v_mov_b32_e32 v34, s0
	v_readlane_b32 s0, v253, 37
	v_cmp_gt_i32_e32 vcc, s3, v50
	v_min_i32_e32 v12, 0x4000, v50
	v_mov_b32_e32 v35, s0
	v_readlane_b32 s0, v253, 40
	v_cndmask_b32_e32 v3, 0, v51, vcc
	v_cndmask_b32_e32 v2, v0, v50, vcc
	v_mov_b32_e32 v36, s0
	v_readlane_b32 s0, v253, 38
	v_cndmask_b32_e32 v5, v34, v35, vcc
	v_lshlrev_b64 v[2:3], 12, v[2:3]
	v_mov_b32_e32 v37, s0
	v_cndmask_b32_e32 v4, v36, v37, vcc
	v_lshl_add_u64 v[2:3], v[4:5], 0, v[2:3]
	v_lshlrev_b32_e32 v0, 2, v52
	v_lshl_add_u64 v[2:3], v[2:3], 0, v[0:1]
	global_load_dwordx4 v[30:33], v[2:3], off nt
	global_load_dwordx4 v[26:29], v[2:3], off offset:1024 nt
	s_waitcnt lgkmcnt(0)
	global_load_dwordx4 v[18:21], v[2:3], off offset:2048 nt
	s_nop 0
	global_load_dwordx4 v[2:5], v[2:3], off offset:3072 nt
	s_nop 0
	global_load_dwordx4 v[80:83], v[54:55], off
	v_lshl_add_u64 v[10:11], s[42:43], 0, v[50:51]
	v_ashrrev_i32_e32 v12, 11, v12
	v_readlane_b32 s0, v253, 41
	v_mov_b64_e32 v[6:7], s[36:37]
	v_lshl_add_u64 v[70:71], s[42:43], 0, v[10:11]
	v_add_u32_e32 v11, s0, v12
	s_movk_i32 s0, 0x3000
	v_mad_i64_i32 v[6:7], s[0:1], v11, s0, v[6:7]
	s_mov_b64 s[0:1], 0x1000
	s_nop 0
	v_lshl_add_u64 v[92:93], v[6:7], 0, s[0:1]
	v_lshl_add_u64 v[12:13], v[92:93], 0, v[0:1]
	global_load_dwordx4 v[84:87], v[12:13], off
	v_lshl_add_u64 v[94:95], v[6:7], 0, v[0:1]
	global_load_dwordx4 v[88:91], v[94:95], off
	v_mov_b32_e32 v65, v1
	v_mov_b32_e32 v67, v1
	v_mov_b32_e32 v69, v1
	global_load_dwordx4 v[98:101], v[54:55], off offset:1024
	v_lshl_add_u64 v[102:103], v[92:93], 0, v[64:65]
	global_load_dwordx4 v[102:105], v[102:103], off
	global_load_dwordx4 v[106:109], v[94:95], off offset:1024
	global_load_dwordx4 v[110:113], v[54:55], off offset:2048
	v_lshl_add_u64 v[114:115], v[92:93], 0, v[66:67]
	global_load_dwordx4 v[114:117], v[114:115], off
	global_load_dwordx4 v[118:121], v[94:95], off offset:2048
	global_load_dwordx4 v[122:125], v[54:55], off offset:3072
	v_lshl_add_u64 v[126:127], v[92:93], 0, v[68:69]
	global_load_dwordx4 v[126:129], v[126:127], off
	global_load_dwordx4 v[130:133], v[94:95], off offset:3072
	s_movk_i32 s2, 0x4800
	v_cmp_gt_i32_e64 s[4:5], s2, v10
	v_cmp_gt_i32_e32 vcc, s2, v70
	s_nop 1
	v_cndmask_b32_e64 v168, v50, v10, s[4:5]
	v_cndmask_b32_e32 v169, v50, v70, vcc
	v_cmp_gt_i32_e64 s[4:5], s3, v168
	v_cmp_gt_i32_e32 vcc, s3, v169
	v_ashrrev_i32_e32 v171, 31, v168
	v_add_u32_e32 v170, 0xffffc000, v168
	v_ashrrev_i32_e32 v175, 31, v169
	v_add_u32_e32 v174, 0xffffc000, v169
	v_cndmask_b32_e64 v171, 0, v171, s[4:5]
	v_cndmask_b32_e64 v170, v170, v168, s[4:5]
	v_cndmask_b32_e64 v173, v34, v35, s[4:5]
	v_cndmask_b32_e64 v172, v36, v37, s[4:5]
	v_cndmask_b32_e32 v175, 0, v175, vcc
	v_cndmask_b32_e32 v174, v174, v169, vcc
	v_cndmask_b32_e32 v177, v34, v35, vcc
	v_cndmask_b32_e32 v176, v36, v37, vcc
	v_lshlrev_b64 v[170:171], 12, v[170:171]
	v_lshlrev_b64 v[174:175], 12, v[174:175]
	v_lshl_add_u64 v[170:171], v[172:173], 0, v[170:171]
	v_lshl_add_u64 v[174:175], v[176:177], 0, v[174:175]
	v_lshl_add_u64 v[170:171], v[170:171], 0, v[0:1]
	v_lshl_add_u64 v[174:175], v[174:175], 0, v[0:1]
	global_load_dwordx4 v[134:137], v[170:171], off nt
	global_load_dwordx4 v[138:141], v[170:171], off offset:1024 nt
	global_load_dwordx4 v[142:145], v[170:171], off offset:2048 nt
	global_load_dwordx4 v[146:149], v[170:171], off offset:3072 nt
	global_load_dwordx4 v[150:153], v[174:175], off nt
	global_load_dwordx4 v[154:157], v[174:175], off offset:1024 nt
	global_load_dwordx4 v[158:161], v[174:175], off offset:2048 nt
	global_load_dwordx4 v[164:167], v[174:175], off offset:3072 nt
	v_lshl_add_u64 v[8:9], v[62:63], 0, v[58:59]
	s_mov_b32 s0, 0x133c000
	v_add_co_u32_e32 v72, vcc, s0, v8
	s_movk_i32 s2, 0x4800
	s_nop 0
	v_addc_co_u32_e32 v73, vcc, 0, v9, vcc
	v_cmp_gt_i32_e64 s[0:1], s2, v10
	v_cmp_gt_i32_e32 vcc, s2, v70
	v_mov_b32_e32 v65, v1
	v_cndmask_b32_e64 v38, v50, v10, s[0:1]
	v_ashrrev_i32_e32 v39, 31, v38
	v_add_u32_e32 v40, 0xffffc000, v38
	v_cmp_gt_i32_e64 s[4:5], s3, v38
	s_waitcnt vmcnt(14)
	v_mov_b32_e32 v8, v31
	s_waitcnt vmcnt(13)
	v_mov_b32_e32 v9, v27
	v_mov_b32_e32 v6, v30
	v_mov_b32_e32 v7, v26
	s_waitcnt vmcnt(12)
	v_mov_b32_e32 v14, v19
	s_waitcnt vmcnt(11)
	v_mov_b32_e32 v15, v3
	v_pk_mul_f32 v[8:9], v[8:9], v[8:9]
	v_mov_b32_e32 v10, v32
	v_mov_b32_e32 v11, v28
	v_mov_b32_e32 v12, v18
	v_mov_b32_e32 v13, v2
	v_pk_mul_f32 v[14:15], v[14:15], v[14:15]
	v_pk_fma_f32 v[6:7], v[6:7], v[6:7], v[8:9]
	v_mov_b32_e32 v16, v33
	v_mov_b32_e32 v17, v29
	v_mov_b32_e32 v22, v20
	v_mov_b32_e32 v23, v4
	v_pk_fma_f32 v[8:9], v[12:13], v[12:13], v[14:15]
	v_pk_fma_f32 v[6:7], v[10:11], v[10:11], v[6:7]
	v_mov_b32_e32 v24, v21
	v_mov_b32_e32 v25, v5
	v_pk_fma_f32 v[8:9], v[22:23], v[22:23], v[8:9]
	v_pk_fma_f32 v[6:7], v[16:17], v[16:17], v[6:7]
	v_pk_fma_f32 v[8:9], v[24:25], v[24:25], v[8:9]
	v_add_f32_e32 v6, v6, v7
	v_add_f32_e32 v6, v6, v8
	v_add_f32_e32 v8, v6, v9
	v_mov_b32_e32 v9, v8
	s_nop 1
	v_permlane32_swap_b32_e32 v8, v9
	v_cndmask_b32_e32 v10, v50, v70, vcc
	v_cndmask_b32_e64 v7, 0, v39, s[4:5]
	v_cndmask_b32_e64 v6, v40, v38, s[4:5]
	v_add_u32_e32 v14, 0xffffc000, v10
	s_waitcnt lgkmcnt(0)
	v_add_f32_e32 v11, v8, v9
	v_mov_b32_e32 v12, v11
	s_nop 1
	v_permlane16_swap_b32_e32 v11, v12
	v_cndmask_b32_e64 v9, v34, v35, s[4:5]
	v_cndmask_b32_e64 v8, v36, v37, s[4:5]
	v_cmp_gt_i32_e64 s[4:5], s3, v10
	v_ashrrev_i32_e32 v13, 31, v10
	s_waitcnt lgkmcnt(0)
	v_add_f32_e32 v15, v11, v12
	s_nop 1
	v_mov_b32_dpp v16, v15 row_ror:8 row_mask:0xf bank_mask:0xf
	v_cndmask_b32_e64 v10, v14, v10, s[4:5]
	v_cndmask_b32_e64 v11, 0, v13, s[4:5]
	v_lshlrev_b64 v[6:7], 12, v[6:7]
	v_lshl_add_u64 v[6:7], v[8:9], 0, v[6:7]
	s_waitcnt lgkmcnt(0)
	v_add_f32_e32 v14, v15, v16
	s_nop 1
	v_mov_b32_dpp v15, v14 row_ror:4 row_mask:0xf bank_mask:0xf
	v_lshlrev_b64 v[8:9], 12, v[10:11]
	v_cndmask_b32_e64 v13, v34, v35, s[4:5]
	v_cndmask_b32_e64 v12, v36, v37, s[4:5]
	v_lshl_add_u64 v[8:9], v[12:13], 0, v[8:9]
	s_waitcnt lgkmcnt(0)
	v_add_f32_e32 v10, v14, v15
	s_nop 1
	v_mov_b32_dpp v11, v10 quad_perm:[2,3,0,1] row_mask:0xf bank_mask:0xf
	v_lshl_add_u64 v[6:7], v[6:7], 0, v[0:1]
	v_lshl_add_u64 v[8:9], v[8:9], 0, v[0:1]
	s_waitcnt vmcnt(0)
	v_mov_b64_e32 v[46:47], v[134:135]
	v_mov_b64_e32 v[48:49], v[136:137]
	v_mov_b64_e32 v[42:43], v[138:139]
	v_mov_b64_e32 v[44:45], v[140:141]
	v_mov_b64_e32 v[38:39], v[142:143]
	v_mov_b64_e32 v[40:41], v[144:145]
	v_mov_b64_e32 v[34:35], v[146:147]
	v_mov_b64_e32 v[36:37], v[148:149]
	v_mov_b64_e32 v[22:23], v[150:151]
	v_mov_b64_e32 v[24:25], v[152:153]
	v_mov_b64_e32 v[14:15], v[154:155]
	v_mov_b64_e32 v[16:17], v[156:157]
	s_waitcnt lgkmcnt(0)
	v_add_f32_e32 v10, v10, v11
	s_nop 1
	v_mov_b32_dpp v11, v10 quad_perm:[1,0,3,2] row_mask:0xf bank_mask:0xf
	s_waitcnt vmcnt(7)
	v_pk_add_f32 v[84:85], v[84:85], 1.0 op_sel_hi:[1,0]
	v_pk_add_f32 v[86:87], v[86:87], 1.0 op_sel_hi:[1,0]
	s_waitcnt lgkmcnt(0)
	v_add_f32_e32 v6, v10, v11
	v_fmamk_f32 v6, v6, 0x3a800000, v196
	v_mul_f32_e32 v7, 0x4b800000, v6
	v_cmp_gt_f32_e64 s[4:5], s33, v6
	s_waitcnt vmcnt(1)
	v_mul_f32_e32 v71, v23, v23
	v_cndmask_b32_e64 v6, v6, v7, s[4:5]
	v_rsq_f32_e32 v67, v6
	v_mov_b64_e32 v[10:11], v[158:159]
	v_mov_b64_e32 v[12:13], v[160:161]
	v_mov_b64_e32 v[6:7], v[164:165]
	v_mov_b64_e32 v[8:9], v[166:167]
	s_waitcnt vmcnt(2)
	v_mul_f32_e32 v79, v15, v15
	v_fmac_f32_e32 v71, v22, v22
	v_mul_f32_e32 v69, 0x45800000, v67
	v_cndmask_b32_e64 v96, v67, v69, s[4:5]
	v_pk_mul_f32 v[30:31], v[30:31], v[96:97] op_sel_hi:[1,0]
	v_pk_mul_f32 v[32:33], v[32:33], v[96:97] op_sel_hi:[1,0]
	v_pk_mul_f32 v[30:31], v[30:31], v[80:81]
	v_pk_mul_f32 v[32:33], v[32:33], v[82:83]
	v_pk_fma_f32 v[30:31], v[30:31], v[84:85], v[88:89]
	v_pk_fma_f32 v[32:33], v[32:33], v[86:87], v[90:91]
	v_cvt_pk_bf16_f32 v30, v30, v31
	v_cvt_pk_bf16_f32 v31, v32, v33
	global_store_dwordx2 v[72:73], v[30:31], off nt
	s_nop 0
	v_pk_mul_f32 v[26:27], v[26:27], v[96:97] op_sel_hi:[1,0]
	v_pk_mul_f32 v[28:29], v[28:29], v[96:97] op_sel_hi:[1,0]
	v_mov_b32_e32 v67, v1
	v_pk_mul_f32 v[18:19], v[18:19], v[96:97] op_sel_hi:[1,0]
	v_pk_mul_f32 v[20:21], v[20:21], v[96:97] op_sel_hi:[1,0]
	v_mov_b32_e32 v69, v1
	v_fmac_f32_e32 v79, v14, v14
	v_fmac_f32_e32 v71, v24, v24
	v_fmac_f32_e32 v79, v16, v16
	v_fmac_f32_e32 v71, v25, v25
	v_fmac_f32_e32 v79, v17, v17
	v_pk_mul_f32 v[2:3], v[2:3], v[96:97] op_sel_hi:[1,0]
	v_pk_mul_f32 v[4:5], v[4:5], v[96:97] op_sel_hi:[1,0]
	s_waitcnt vmcnt(2)
	v_pk_mul_f32 v[26:27], v[26:27], v[98:99]
	v_pk_mul_f32 v[28:29], v[28:29], v[100:101]
	s_waitcnt vmcnt(1)
	v_pk_add_f32 v[30:31], v[102:103], 1.0 op_sel_hi:[1,0]
	v_pk_add_f32 v[32:33], v[104:105], 1.0 op_sel_hi:[1,0]
	s_waitcnt vmcnt(0)
	v_pk_fma_f32 v[26:27], v[26:27], v[30:31], v[106:107]
	v_pk_fma_f32 v[28:29], v[28:29], v[32:33], v[108:109]
	v_cvt_pk_bf16_f32 v26, v26, v27
	v_cvt_pk_bf16_f32 v27, v28, v29
	global_store_dwordx2 v[72:73], v[26:27], off offset:512 nt
	s_nop 0
	s_waitcnt vmcnt(2)
	v_pk_mul_f32 v[18:19], v[18:19], v[110:111]
	v_pk_mul_f32 v[20:21], v[20:21], v[112:113]
	s_waitcnt vmcnt(1)
	v_pk_add_f32 v[26:27], v[114:115], 1.0 op_sel_hi:[1,0]
	v_pk_add_f32 v[28:29], v[116:117], 1.0 op_sel_hi:[1,0]
	s_waitcnt vmcnt(0)
	v_pk_fma_f32 v[18:19], v[18:19], v[26:27], v[118:119]
	v_pk_fma_f32 v[20:21], v[20:21], v[28:29], v[120:121]
	v_cvt_pk_bf16_f32 v18, v18, v19
	v_cvt_pk_bf16_f32 v19, v20, v21
	global_store_dwordx2 v[72:73], v[18:19], off offset:1024 nt
	v_mul_f32_e32 v18, v47, v47
	v_mul_f32_e32 v19, v43, v43
	v_mul_f32_e32 v20, v39, v39
	v_fmac_f32_e32 v18, v46, v46
	v_fmac_f32_e32 v19, v42, v42
	v_mul_f32_e32 v84, v11, v11
	v_mul_f32_e32 v21, v35, v35
	v_fmac_f32_e32 v20, v38, v38
	v_mul_f32_e32 v85, v7, v7
	v_fmac_f32_e32 v18, v48, v48
	v_fmac_f32_e32 v19, v44, v44
	v_fmac_f32_e32 v84, v10, v10
	v_fmac_f32_e32 v21, v34, v34
	v_fmac_f32_e32 v20, v40, v40
	v_fmac_f32_e32 v85, v6, v6
	v_fmac_f32_e32 v18, v49, v49
	v_fmac_f32_e32 v19, v45, v45
	v_fmac_f32_e32 v84, v12, v12
	v_fmac_f32_e32 v21, v36, v36
	v_fmac_f32_e32 v20, v41, v41
	v_fmac_f32_e32 v85, v8, v8
	v_add_f32_e32 v18, v18, v19
	v_fmac_f32_e32 v84, v13, v13
	v_add_f32_e32 v19, v71, v79
	v_fmac_f32_e32 v21, v37, v37
	v_fmac_f32_e32 v85, v9, v9
	v_add_f32_e32 v18, v18, v20
	v_add_f32_e32 v19, v19, v84
	v_add_f32_e32 v18, v18, v21
	v_add_f32_e32 v19, v19, v85
	v_mov_b32_e32 v20, v18
	s_nop 1
	v_permlane32_swap_b32_e32 v18, v20
	v_mov_b32_e32 v21, v19
	s_nop 1
	v_permlane32_swap_b32_e32 v19, v21
	s_waitcnt lgkmcnt(1)
	v_add_f32_e32 v18, v18, v20
	s_waitcnt lgkmcnt(0)
	v_add_f32_e32 v19, v19, v21
	v_mov_b32_e32 v20, v18
	s_nop 1
	v_permlane16_swap_b32_e32 v18, v20
	v_mov_b32_e32 v21, v19
	s_nop 1
	v_permlane16_swap_b32_e32 v19, v21
	s_waitcnt lgkmcnt(1)
	v_add_f32_e32 v18, v18, v20
	s_waitcnt lgkmcnt(0)
	v_add_f32_e32 v19, v19, v21
	v_mov_b32_dpp v20, v18 row_ror:8 row_mask:0xf bank_mask:0xf
	s_nop 0
	v_mov_b32_dpp v21, v19 row_ror:8 row_mask:0xf bank_mask:0xf
	s_waitcnt lgkmcnt(1)
	v_add_f32_e32 v18, v18, v20
	s_waitcnt lgkmcnt(0)
	v_add_f32_e32 v19, v19, v21
	v_mov_b32_dpp v20, v18 row_ror:4 row_mask:0xf bank_mask:0xf
	s_nop 0
	v_mov_b32_dpp v21, v19 row_ror:4 row_mask:0xf bank_mask:0xf
	s_waitcnt lgkmcnt(1)
	v_add_f32_e32 v18, v18, v20
	s_waitcnt lgkmcnt(0)
	v_add_f32_e32 v19, v19, v21
	v_mov_b32_dpp v20, v18 quad_perm:[2,3,0,1] row_mask:0xf bank_mask:0xf
	s_nop 0
	v_mov_b32_dpp v21, v19 quad_perm:[2,3,0,1] row_mask:0xf bank_mask:0xf
	s_waitcnt lgkmcnt(1)
	v_add_f32_e32 v20, v18, v20
	s_waitcnt lgkmcnt(0)
	v_add_f32_e32 v18, v19, v21
	v_mov_b32_dpp v21, v20 quad_perm:[1,0,3,2] row_mask:0xf bank_mask:0xf
	s_nop 0
	v_mov_b32_dpp v19, v18 quad_perm:[1,0,3,2] row_mask:0xf bank_mask:0xf
	s_waitcnt vmcnt(2)
	v_pk_mul_f32 v[2:3], v[2:3], v[122:123]
	v_pk_mul_f32 v[4:5], v[4:5], v[124:125]
	s_waitcnt vmcnt(1)
	v_pk_add_f32 v[26:27], v[126:127], 1.0 op_sel_hi:[1,0]
	v_pk_add_f32 v[28:29], v[128:129], 1.0 op_sel_hi:[1,0]
	s_waitcnt vmcnt(0)
	v_pk_fma_f32 v[2:3], v[2:3], v[26:27], v[130:131]
	v_pk_fma_f32 v[4:5], v[4:5], v[28:29], v[132:133]
	v_cvt_pk_bf16_f32 v2, v2, v3
	v_cvt_pk_bf16_f32 v3, v4, v5
	global_store_dwordx2 v[72:73], v[2:3], off offset:1536 nt
	s_and_saveexec_b64 s[12:13], s[0:1]
	s_cbranch_execz .LBB0_182
	v_add_u32_e32 v2, s42, v50
	v_min_i32_e32 v2, 0x4000, v2
	v_ashrrev_i32_e32 v2, 11, v2
	v_readlane_b32 s0, v253, 41
	s_waitcnt lgkmcnt(1)
	v_add_f32_e32 v71, v20, v21
	v_fmamk_f32 v71, v71, 0x3a800000, v196
	v_add_u32_e32 v4, s0, v2
	v_mov_b64_e32 v[2:3], s[36:37]
	s_movk_i32 s0, 0x3000
	v_mad_i64_i32 v[30:31], s[0:1], v4, s0, v[2:3]
	s_mov_b64 s[0:1], 0x1000
	s_nop 0
	v_lshl_add_u64 v[72:73], v[30:31], 0, s[0:1]
	v_lshl_add_u64 v[26:27], v[72:73], 0, v[0:1]
	global_load_dwordx4 v[2:5], v[54:55], off
	v_lshl_add_u64 v[80:81], v[30:31], 0, v[0:1]
	global_load_dwordx4 v[26:29], v[26:27], off
	v_mul_f32_e32 v79, 0x4b800000, v71
	global_load_dwordx4 v[30:33], v[80:81], off
	v_mov_b32_e32 v65, v1
	v_mov_b32_e32 v67, v1
	v_mov_b32_e32 v69, v1
	global_load_dwordx4 v[98:101], v[54:55], off offset:1024
	v_lshl_add_u64 v[102:103], v[72:73], 0, v[64:65]
	global_load_dwordx4 v[102:105], v[102:103], off
	global_load_dwordx4 v[106:109], v[80:81], off offset:1024
	global_load_dwordx4 v[110:113], v[54:55], off offset:2048
	v_lshl_add_u64 v[114:115], v[72:73], 0, v[66:67]
	global_load_dwordx4 v[114:117], v[114:115], off
	global_load_dwordx4 v[118:121], v[80:81], off offset:2048
	global_load_dwordx4 v[122:125], v[54:55], off offset:3072
	v_lshl_add_u64 v[126:127], v[72:73], 0, v[68:69]
	global_load_dwordx4 v[126:129], v[126:127], off
	global_load_dwordx4 v[130:133], v[80:81], off offset:3072
	v_cmp_gt_f32_e64 s[0:1], s33, v71
	v_lshl_add_u64 v[20:21], v[60:61], 0, v[58:59]
	v_cndmask_b32_e64 v71, v71, v79, s[0:1]
	v_rsq_f32_e32 v71, v71
	s_mov_b32 s2, 0x133c000
	v_add_co_u32_e64 v20, s[4:5], s2, v20
	v_mul_f32_e32 v65, 0x45800000, v71
	v_cndmask_b32_e64 v84, v71, v65, s[0:1]
	v_pk_mul_f32 v[46:47], v[46:47], v[84:85] op_sel_hi:[1,0]
	v_pk_mul_f32 v[48:49], v[48:49], v[84:85] op_sel_hi:[1,0]
	v_addc_co_u32_e64 v21, s[4:5], 0, v21, s[4:5]
	v_pk_mul_f32 v[42:43], v[42:43], v[84:85] op_sel_hi:[1,0]
	v_pk_mul_f32 v[44:45], v[44:45], v[84:85] op_sel_hi:[1,0]
	v_pk_mul_f32 v[38:39], v[38:39], v[84:85] op_sel_hi:[1,0]
	v_pk_mul_f32 v[40:41], v[40:41], v[84:85] op_sel_hi:[1,0]
	v_pk_mul_f32 v[34:35], v[34:35], v[84:85] op_sel_hi:[1,0]
	v_pk_mul_f32 v[36:37], v[36:37], v[84:85] op_sel_hi:[1,0]
	s_waitcnt vmcnt(2)
	v_pk_mul_f32 v[2:3], v[46:47], v[2:3]
	v_pk_mul_f32 v[4:5], v[48:49], v[4:5]
	s_waitcnt vmcnt(1)
	v_pk_add_f32 v[26:27], v[26:27], 1.0 op_sel_hi:[1,0]
	v_pk_add_f32 v[28:29], v[28:29], 1.0 op_sel_hi:[1,0]
	s_waitcnt vmcnt(0)
	v_pk_fma_f32 v[2:3], v[2:3], v[26:27], v[30:31]
	v_pk_fma_f32 v[4:5], v[4:5], v[28:29], v[32:33]
	v_cvt_pk_bf16_f32 v2, v2, v3
	v_cvt_pk_bf16_f32 v3, v4, v5
	global_store_dwordx2 v[20:21], v[2:3], off nt
	s_nop 0
	s_waitcnt vmcnt(2)
	v_pk_mul_f32 v[2:3], v[42:43], v[98:99]
	s_waitcnt vmcnt(1)
	v_pk_add_f32 v[26:27], v[102:103], 1.0 op_sel_hi:[1,0]
	v_pk_mul_f32 v[4:5], v[44:45], v[100:101]
	v_pk_add_f32 v[28:29], v[104:105], 1.0 op_sel_hi:[1,0]
	s_waitcnt vmcnt(0)
	v_pk_fma_f32 v[2:3], v[2:3], v[26:27], v[106:107]
	v_pk_fma_f32 v[4:5], v[4:5], v[28:29], v[108:109]
	v_cvt_pk_bf16_f32 v2, v2, v3
	v_cvt_pk_bf16_f32 v3, v4, v5
	global_store_dwordx2 v[20:21], v[2:3], off offset:512 nt
	s_nop 0
	s_waitcnt vmcnt(2)
	v_pk_mul_f32 v[2:3], v[38:39], v[110:111]
	s_waitcnt vmcnt(1)
	v_pk_add_f32 v[26:27], v[114:115], 1.0 op_sel_hi:[1,0]
	v_pk_mul_f32 v[4:5], v[40:41], v[112:113]
	v_pk_add_f32 v[28:29], v[116:117], 1.0 op_sel_hi:[1,0]
	s_waitcnt vmcnt(0)
	v_pk_fma_f32 v[2:3], v[2:3], v[26:27], v[118:119]
	v_pk_fma_f32 v[4:5], v[4:5], v[28:29], v[120:121]
	v_cvt_pk_bf16_f32 v2, v2, v3
	v_cvt_pk_bf16_f32 v3, v4, v5
	global_store_dwordx2 v[20:21], v[2:3], off offset:1024 nt
	s_nop 0
	s_waitcnt vmcnt(2)
	v_pk_mul_f32 v[2:3], v[34:35], v[122:123]
	s_waitcnt vmcnt(1)
	v_pk_add_f32 v[26:27], v[126:127], 1.0 op_sel_hi:[1,0]
	v_pk_mul_f32 v[4:5], v[36:37], v[124:125]
	v_pk_add_f32 v[28:29], v[128:129], 1.0 op_sel_hi:[1,0]
	s_waitcnt vmcnt(0)
	v_pk_fma_f32 v[2:3], v[2:3], v[26:27], v[130:131]
	v_pk_fma_f32 v[4:5], v[4:5], v[28:29], v[132:133]
	v_cvt_pk_bf16_f32 v2, v2, v3
	v_cvt_pk_bf16_f32 v3, v4, v5
	global_store_dwordx2 v[20:21], v[2:3], off offset:1536 nt
.LBB0_182:
	s_or_b64 exec, exec, s[12:13]
	s_and_saveexec_b64 s[0:1], vcc
	s_cbranch_execz .LBB0_179
	v_readlane_b32 s2, v255, 5
	v_mov_b32_e32 v65, v1
	v_mov_b32_e32 v67, v1
	v_add_u32_e32 v20, s2, v50
	v_min_i32_e32 v2, 0x4000, v20
	v_ashrrev_i32_e32 v2, 11, v2
	v_readlane_b32 s2, v253, 41
	s_waitcnt lgkmcnt(1)
	v_ashrrev_i32_e32 v21, 31, v20
	v_mov_b32_e32 v69, v1
	v_add_u32_e32 v4, s2, v2
	v_mov_b64_e32 v[2:3], s[36:37]
	s_movk_i32 s2, 0x3000
	v_mad_i64_i32 v[30:31], s[2:3], v4, s2, v[2:3]
	s_mov_b64 s[2:3], 0x1000
	s_nop 0
	v_lshl_add_u64 v[34:35], v[30:31], 0, s[2:3]
	v_lshl_add_u64 v[26:27], v[34:35], 0, v[0:1]
	global_load_dwordx4 v[2:5], v[54:55], off
	v_lshl_add_u64 v[36:37], v[30:31], 0, v[0:1]
	global_load_dwordx4 v[26:29], v[26:27], off
	s_waitcnt lgkmcnt(0)
	v_add_f32_e32 v0, v18, v19
	global_load_dwordx4 v[30:33], v[36:37], off
	v_mov_b32_e32 v65, v1
	v_mov_b32_e32 v67, v1
	v_mov_b32_e32 v69, v1
	global_load_dwordx4 v[98:101], v[54:55], off offset:1024
	v_lshl_add_u64 v[102:103], v[34:35], 0, v[64:65]
	global_load_dwordx4 v[102:105], v[102:103], off
	global_load_dwordx4 v[106:109], v[36:37], off offset:1024
	global_load_dwordx4 v[110:113], v[54:55], off offset:2048
	v_lshl_add_u64 v[114:115], v[34:35], 0, v[66:67]
	global_load_dwordx4 v[114:117], v[114:115], off
	global_load_dwordx4 v[118:121], v[36:37], off offset:2048
	global_load_dwordx4 v[122:125], v[54:55], off offset:3072
	v_lshl_add_u64 v[126:127], v[34:35], 0, v[68:69]
	global_load_dwordx4 v[126:129], v[126:127], off
	global_load_dwordx4 v[130:133], v[36:37], off offset:3072
	v_fmamk_f32 v0, v0, 0x3a800000, v196
	v_mul_f32_e32 v18, 0x4b800000, v0
	v_cmp_gt_f32_e32 vcc, s33, v0
	s_nop 1
	v_cndmask_b32_e32 v0, v0, v18, vcc
	v_rsq_f32_e32 v0, v0
	v_lshlrev_b64 v[18:19], 11, v[20:21]
	v_lshl_add_u64 v[38:39], v[56:57], 0, v[18:19]
	v_mul_f32_e32 v20, 0x45800000, v0
	v_cndmask_b32_e32 v0, v0, v20, vcc
	v_pk_mul_f32 v[20:21], v[22:23], v[0:1] op_sel_hi:[1,0]
	v_pk_mul_f32 v[22:23], v[24:25], v[0:1] op_sel_hi:[1,0]
	v_pk_mul_f32 v[14:15], v[14:15], v[0:1] op_sel_hi:[1,0]
	v_pk_mul_f32 v[16:17], v[16:17], v[0:1] op_sel_hi:[1,0]
	v_pk_mul_f32 v[10:11], v[10:11], v[0:1] op_sel_hi:[1,0]
	v_pk_mul_f32 v[12:13], v[12:13], v[0:1] op_sel_hi:[1,0]
	v_pk_mul_f32 v[6:7], v[6:7], v[0:1] op_sel_hi:[1,0]
	v_pk_mul_f32 v[8:9], v[8:9], v[0:1] op_sel_hi:[1,0]
	s_waitcnt vmcnt(2)
	v_pk_mul_f32 v[2:3], v[20:21], v[2:3]
	v_pk_mul_f32 v[4:5], v[22:23], v[4:5]
	s_waitcnt vmcnt(1)
	v_pk_add_f32 v[20:21], v[26:27], 1.0 op_sel_hi:[1,0]
	v_pk_add_f32 v[22:23], v[28:29], 1.0 op_sel_hi:[1,0]
	s_waitcnt vmcnt(0)
	v_pk_fma_f32 v[2:3], v[2:3], v[20:21], v[30:31]
	v_pk_fma_f32 v[4:5], v[4:5], v[22:23], v[32:33]
	v_cvt_pk_bf16_f32 v2, v2, v3
	v_cvt_pk_bf16_f32 v3, v4, v5
	global_store_dwordx2 v[38:39], v[2:3], off nt
	s_nop 0
	s_nop 0
	s_waitcnt vmcnt(2)
	v_pk_mul_f32 v[2:3], v[14:15], v[98:99]
	s_waitcnt vmcnt(1)
	v_pk_add_f32 v[14:15], v[102:103], 1.0 op_sel_hi:[1,0]
	v_pk_mul_f32 v[4:5], v[16:17], v[100:101]
	v_pk_add_f32 v[16:17], v[104:105], 1.0 op_sel_hi:[1,0]
	s_waitcnt vmcnt(0)
	v_pk_fma_f32 v[2:3], v[2:3], v[14:15], v[106:107]
	v_pk_fma_f32 v[4:5], v[4:5], v[16:17], v[108:109]
	v_cvt_pk_bf16_f32 v2, v2, v3
	v_cvt_pk_bf16_f32 v3, v4, v5
	global_store_dwordx2 v[38:39], v[2:3], off offset:512 nt
	s_nop 0
	s_waitcnt vmcnt(2)
	v_pk_mul_f32 v[2:3], v[10:11], v[110:111]
	s_waitcnt vmcnt(1)
	v_pk_add_f32 v[10:11], v[114:115], 1.0 op_sel_hi:[1,0]
	v_pk_mul_f32 v[4:5], v[12:13], v[112:113]
	v_pk_add_f32 v[12:13], v[116:117], 1.0 op_sel_hi:[1,0]
	s_waitcnt vmcnt(0)
	v_pk_fma_f32 v[2:3], v[2:3], v[10:11], v[118:119]
	v_pk_fma_f32 v[4:5], v[4:5], v[12:13], v[120:121]
	v_cvt_pk_bf16_f32 v2, v2, v3
	v_cvt_pk_bf16_f32 v3, v4, v5
	global_store_dwordx2 v[38:39], v[2:3], off offset:1024 nt
	s_nop 0
	s_waitcnt vmcnt(2)
	v_pk_mul_f32 v[2:3], v[6:7], v[122:123]
	s_waitcnt vmcnt(1)
	v_pk_add_f32 v[6:7], v[126:127], 1.0 op_sel_hi:[1,0]
	v_pk_mul_f32 v[4:5], v[8:9], v[124:125]
	v_pk_add_f32 v[8:9], v[128:129], 1.0 op_sel_hi:[1,0]
	s_waitcnt vmcnt(0)
	v_pk_fma_f32 v[2:3], v[2:3], v[6:7], v[130:131]
	v_pk_fma_f32 v[4:5], v[4:5], v[8:9], v[132:133]
	v_cvt_pk_bf16_f32 v2, v2, v3
	v_cvt_pk_bf16_f32 v3, v4, v5
	global_store_dwordx2 v[38:39], v[2:3], off offset:1536 nt
	s_branch .LBB0_179
